# ret_out unit epilogue: chunks 1-7 hand-written (batched gate/gain loads, silu via v_rcp_f32) and 8 dwordx2 stores paired into 4 dwordx4 (permlane32+16 swaps)
# speedup vs baseline: 1.0253x; 1.0013x over previous
.LBB0_490:
	s_or_b64 exec, exec, s[0:1]
	v_lshlrev_b32_e32 v70, 7, v6
	v_lshlrev_b32_e32 v2, 3, v5
	v_ashrrev_i32_e32 v71, 31, v70
	v_and_b32_e32 v7, 56, v2
	v_bfe_u32 v13, v5, 3, 5
	v_lshlrev_b64 v[72:73], 1, v[70:71]
	v_lshlrev_b32_e32 v0, 3, v7
	v_mov_b32_e32 v1, v65
	v_or_b32_e32 v8, v3, v13
	v_lshl_add_u64 v[0:1], s[40:41], 0, v[0:1]
	v_lshlrev_b32_e32 v8, 9, v8
	v_mov_b32_e32 v9, v65
	v_lshl_add_u64 v[18:19], s[38:39], 0, v[72:73]
	v_lshlrev_b32_e32 v64, 1, v7
	v_lshl_add_u64 v[38:39], v[0:1], 0, v[8:9]
	v_lshl_add_u64 v[42:43], v[18:19], 0, v[64:65]
	v_add_u32_e32 v7, v68, v13
	global_load_dwordx4 v[8:11], v[38:39], off
	global_load_dwordx4 v[14:17], v[38:39], off offset:16
	global_load_dwordx4 v[18:21], v[38:39], off offset:32
	v_mad_i64_i32 v[34:35], s[0:1], v7, s57, v[42:43]
	global_load_dwordx4 v[22:25], v[34:35], off
	global_load_dwordx4 v[26:29], v[34:35], off offset:128
	global_load_dwordx4 v[30:33], v[34:35], off offset:1536
	s_nop 0
	global_load_dwordx4 v[34:37], v[34:35], off offset:1664
	s_nop 0
	global_load_dwordx4 v[38:41], v[38:39], off offset:48
	v_or_b32_sdwa v140, v5, s61 dst_sel:DWORD dst_unused:UNUSED_PAD src0_sel:BYTE_0 src1_sel:DWORD
	v_lshrrev_b32_e32 v141, 3, v140
	v_add_u32_e32 v142, v68, v141
	v_mad_i64_i32 v[134:135], s[0:1], v142, s57, v[42:43]
	v_or_b32_e32 v143, v3, v141
	v_lshlrev_b32_e32 v136, 9, v143
	v_mov_b32_e32 v137, v65
	v_lshl_add_u64 v[136:137], v[0:1], 0, v[136:137]
	global_load_dwordx4 v[160:163], v[134:135], off
	global_load_dwordx4 v[164:167], v[134:135], off offset:128
	global_load_dwordx4 v[168:171], v[134:135], off offset:1536
	global_load_dwordx4 v[172:175], v[134:135], off offset:1664
	global_load_dwordx4 v[176:179], v[136:137], off
	global_load_dwordx4 v[180:183], v[136:137], off offset:16
	global_load_dwordx4 v[184:187], v[136:137], off offset:32
	global_load_dwordx4 v[188:191], v[136:137], off offset:48
	v_bfe_u32 v140, v5, 4, 4
	v_add_u32_e32 v140, v68, v140
	v_mad_i64_i32 v[138:139], s[0:1], v140, s57, v[66:67]
	v_lshl_add_u64 v[138:139], v[138:139], 0, v[72:73]
	v_lshlrev_b32_e32 v140, 3, v5
	v_and_b32_e32 v140, 0x78, v140
	v_lshlrev_b32_e32 v140, 1, v140
	v_mov_b32_e32 v141, v65
	v_lshl_add_u64 v[138:139], v[138:139], 0, v[140:141]
	v_mov_b32_e32 v140, 0x1a000
	global_load_dwordx4 v[192:195], v[138:139], off offset:3072
	v_lshl_add_u64 v[138:139], v[138:139], 0, v[140:141]
	global_load_dwordx4 v[196:199], v[138:139], off offset:3072
	v_lshl_add_u64 v[138:139], v[138:139], 0, v[140:141]
	global_load_dwordx4 v[200:203], v[138:139], off offset:3072
	v_lshl_add_u64 v[138:139], v[138:139], 0, v[140:141]
	global_load_dwordx4 v[204:207], v[138:139], off offset:3072
	v_mul_u32_u24_e32 v7, 0x88, v13
	v_mad_i32_i24 v4, v4, s52, 0
	v_lshlrev_b32_e32 v7, 1, v7
	v_add3_u32 v7, v4, v7, v64
	s_add_i32 s2, s2, s84
	s_waitcnt vmcnt(12) lgkmcnt(0)
	v_mov_b32_e32 v44, v8
	v_mov_b32_e32 v45, v10
	v_mov_b32_e32 v10, v9
	v_mov_b32_e32 v8, v14
	v_mov_b32_e32 v9, v16
	v_mov_b32_e32 v16, v15
	v_mov_b32_e32 v14, v18
	v_mov_b32_e32 v15, v20
	v_mov_b32_e32 v20, v19
	v_lshlrev_b32_e32 v18, 16, v22
	v_and_b32_e32 v19, 0xffff0000, v22
	v_lshlrev_b32_e32 v22, 16, v23
	v_and_b32_e32 v23, 0xffff0000, v23
	v_lshlrev_b32_e32 v48, 16, v26
	v_and_b32_e32 v49, 0xffff0000, v26
	v_lshlrev_b32_e32 v26, 16, v27
	v_and_b32_e32 v27, 0xffff0000, v27
	v_lshlrev_b32_e32 v52, 16, v30
	v_and_b32_e32 v53, 0xffff0000, v30
	v_lshlrev_b32_e32 v30, 16, v31
	v_and_b32_e32 v31, 0xffff0000, v31
	v_lshlrev_b32_e32 v56, 16, v34
	v_and_b32_e32 v57, 0xffff0000, v34
	v_lshlrev_b32_e32 v34, 16, v35
	v_and_b32_e32 v35, 0xffff0000, v35
	v_pk_mul_f32 v[76:77], v[16:17], v[26:27]
	v_pk_mul_f32 v[84:85], v[16:17], v[22:23]
	v_pk_mul_f32 v[86:87], v[16:17], v[34:35]
	v_pk_mul_f32 v[16:17], v[16:17], v[30:31]
	v_lshlrev_b32_e32 v46, 16, v24
	v_and_b32_e32 v47, 0xffff0000, v24
	v_lshlrev_b32_e32 v50, 16, v28
	v_and_b32_e32 v51, 0xffff0000, v28
	v_pk_mul_f32 v[60:61], v[10:11], v[48:49]
	v_pk_mul_f32 v[62:63], v[10:11], v[18:19]
	v_pk_mul_f32 v[74:75], v[10:11], v[56:57]
	v_pk_mul_f32 v[10:11], v[10:11], v[52:53]
	v_pk_fma_f32 v[22:23], v[8:9], v[22:23], v[76:77] neg_lo:[0,0,1] neg_hi:[0,0,1]
	v_pk_fma_f32 v[26:27], v[8:9], v[26:27], v[84:85]
	v_pk_fma_f32 v[30:31], v[8:9], v[30:31], v[86:87] neg_lo:[0,0,1] neg_hi:[0,0,1]
	v_pk_fma_f32 v[8:9], v[8:9], v[34:35], v[16:17]
	v_lshlrev_b32_e32 v58, 16, v36
	v_and_b32_e32 v59, 0xffff0000, v36
	v_pk_mul_f32 v[88:89], v[20:21], v[50:51]
	v_pk_fma_f32 v[18:19], v[44:45], v[18:19], v[60:61] neg_lo:[0,0,1] neg_hi:[0,0,1]
	v_pk_fma_f32 v[48:49], v[44:45], v[48:49], v[62:63]
	v_pk_fma_f32 v[52:53], v[44:45], v[52:53], v[74:75] neg_lo:[0,0,1] neg_hi:[0,0,1]
	v_pk_fma_f32 v[10:11], v[44:45], v[56:57], v[10:11]
	v_pk_mul_f32 v[44:45], v[8:9], s[44:45] op_sel_hi:[1,0]
	v_pk_mul_f32 v[8:9], v[20:21], v[46:47]
	v_lshlrev_b32_e32 v54, 16, v32
	v_and_b32_e32 v55, 0xffff0000, v32
	v_pk_mul_f32 v[34:35], v[10:11], s[44:45] op_sel_hi:[1,0]
	v_pk_fma_f32 v[10:11], v[14:15], v[46:47], v[88:89] neg_lo:[0,0,1] neg_hi:[0,0,1]
	v_pk_fma_f32 v[46:47], v[14:15], v[50:51], v[8:9]
	v_pk_mul_f32 v[8:9], v[20:21], v[58:59]
	v_lshlrev_b32_e32 v28, 16, v29
	v_pk_fma_f32 v[8:9], v[14:15], v[54:55], v[8:9] neg_lo:[0,0,1] neg_hi:[0,0,1]
	v_and_b32_e32 v29, 0xffff0000, v29
	v_pk_mul_f32 v[50:51], v[8:9], s[44:45] op_sel_hi:[1,0]
	v_pk_mul_f32 v[8:9], v[20:21], v[54:55]
	v_lshlrev_b32_e32 v24, 16, v25
	v_pk_fma_f32 v[8:9], v[14:15], v[58:59], v[8:9]
	v_and_b32_e32 v25, 0xffff0000, v25
	v_pk_mul_f32 v[14:15], v[8:9], s[44:45] op_sel_hi:[1,0]
	v_mov_b32_e32 v9, v40
	v_mov_b32_e32 v40, v39
	v_mov_b32_e32 v8, v38
	v_pk_mul_f32 v[20:21], v[40:41], v[28:29]
	v_lshlrev_b32_e32 v36, 16, v37
	v_and_b32_e32 v37, 0xffff0000, v37
	v_pk_fma_f32 v[20:21], v[8:9], v[24:25], v[20:21] neg_lo:[0,0,1] neg_hi:[0,0,1]
	v_pk_mul_f32 v[24:25], v[40:41], v[24:25]
	v_lshlrev_b32_e32 v32, 16, v33
	v_and_b32_e32 v33, 0xffff0000, v33
	v_pk_fma_f32 v[24:25], v[8:9], v[28:29], v[24:25]
	v_pk_mul_f32 v[28:29], v[40:41], v[36:37]
	v_cvt_pk_bf16_f32 v10, v10, v11
	v_pk_fma_f32 v[28:29], v[8:9], v[32:33], v[28:29] neg_lo:[0,0,1] neg_hi:[0,0,1]
	v_pk_mul_f32 v[32:33], v[40:41], v[32:33]
	v_cvt_pk_bf16_f32 v11, v20, v21
	v_pk_fma_f32 v[8:9], v[8:9], v[36:37], v[32:33]
	v_pk_mul_f32 v[16:17], v[52:53], s[44:45] op_sel_hi:[1,0]
	v_pk_mul_f32 v[32:33], v[8:9], s[44:45] op_sel_hi:[1,0]
	v_cvt_pk_bf16_f32 v8, v18, v19
	v_cvt_pk_bf16_f32 v9, v22, v23
	v_pk_mul_f32 v[30:31], v[30:31], s[44:45] op_sel_hi:[1,0]
	v_pk_mul_f32 v[28:29], v[28:29], s[44:45] op_sel_hi:[1,0]
	ds_write_b128 v7, v[8:11]
	v_cvt_pk_bf16_f32 v8, v48, v49
	v_cvt_pk_bf16_f32 v9, v26, v27
	v_cvt_pk_bf16_f32 v10, v46, v47
	v_cvt_pk_bf16_f32 v11, v24, v25
	ds_write_b128 v7, v[8:11] offset:128
	v_cvt_pk_bf16_f32 v8, v16, v17
	v_cvt_pk_bf16_f32 v9, v30, v31
	v_cvt_pk_bf16_f32 v10, v50, v51
	v_cvt_pk_bf16_f32 v11, v28, v29
	ds_write_b128 v7, v[8:11] offset:17408
	v_cvt_pk_bf16_f32 v8, v34, v35
	v_cvt_pk_bf16_f32 v9, v44, v45
	v_cvt_pk_bf16_f32 v10, v14, v15
	v_cvt_pk_bf16_f32 v11, v32, v33
	ds_write_b128 v7, v[8:11] offset:17536
	v_or_b32_sdwa v7, v5, s61 dst_sel:DWORD dst_unused:UNUSED_PAD src0_sel:BYTE_0 src1_sel:DWORD
	v_lshrrev_b32_e32 v13, 3, v7
	v_add_u32_e32 v8, v68, v13
	v_or_b32_e32 v3, v3, v13
	v_mad_i64_i32 v[22:23], s[0:1], v8, s57, v[42:43]
	v_lshlrev_b32_e32 v26, 9, v3
	v_mov_b32_e32 v27, v65
	s_nop 0
	v_lshl_add_u64 v[0:1], v[0:1], 0, v[26:27]
	v_mul_u32_u24_e32 v3, 0x88, v13
	v_lshlrev_b32_e32 v3, 1, v3
	v_add3_u32 v3, v4, v3, v64
	v_lshrrev_b32_e32 v7, 4, v7
	s_waitcnt vmcnt(4) lgkmcnt(0)
	v_mov_b64_e32 v[8:9], v[160:161]
	v_mov_b64_e32 v[10:11], v[162:163]
	v_mov_b64_e32 v[14:15], v[164:165]
	v_mov_b64_e32 v[16:17], v[166:167]
	v_mov_b64_e32 v[18:19], v[168:169]
	v_mov_b64_e32 v[20:21], v[170:171]
	v_mov_b64_e32 v[22:23], v[172:173]
	v_mov_b64_e32 v[24:25], v[174:175]
	v_mov_b64_e32 v[26:27], v[176:177]
	v_mov_b64_e32 v[28:29], v[178:179]
	v_mov_b64_e32 v[30:31], v[180:181]
	v_mov_b64_e32 v[32:33], v[182:183]
	v_mov_b64_e32 v[34:35], v[184:185]
	v_mov_b64_e32 v[36:37], v[186:187]
	v_mov_b64_e32 v[38:39], v[188:189]
	v_mov_b64_e32 v[40:41], v[190:191]
	v_lshlrev_b32_e32 v0, 16, v8
	v_lshlrev_b32_e32 v44, 16, v14
	v_and_b32_e32 v45, 0xffff0000, v14
	v_mov_b32_e32 v57, v28
	v_mov_b32_e32 v28, v27
	v_and_b32_e32 v1, 0xffff0000, v8
	v_mov_b32_e32 v56, v26
	v_pk_mul_f32 v[26:27], v[28:29], v[44:45]
	v_lshlrev_b32_e32 v52, 16, v22
	v_and_b32_e32 v53, 0xffff0000, v22
	v_pk_fma_f32 v[26:27], v[56:57], v[0:1], v[26:27] neg_lo:[0,0,1] neg_hi:[0,0,1]
	v_pk_mul_f32 v[0:1], v[28:29], v[0:1]
	v_lshlrev_b32_e32 v48, 16, v18
	v_and_b32_e32 v49, 0xffff0000, v18
	v_pk_fma_f32 v[0:1], v[56:57], v[44:45], v[0:1]
	v_pk_mul_f32 v[44:45], v[28:29], v[52:53]
	v_lshlrev_b32_e32 v14, 16, v15
	v_and_b32_e32 v15, 0xffff0000, v15
	v_pk_fma_f32 v[44:45], v[56:57], v[48:49], v[44:45] neg_lo:[0,0,1] neg_hi:[0,0,1]
	v_pk_mul_f32 v[28:29], v[28:29], v[48:49]
	v_mov_b32_e32 v49, v32
	v_mov_b32_e32 v32, v31
	v_lshlrev_b32_e32 v8, 16, v9
	v_and_b32_e32 v9, 0xffff0000, v9
	v_mov_b32_e32 v48, v30
	v_pk_mul_f32 v[30:31], v[32:33], v[14:15]
	v_lshlrev_b32_e32 v22, 16, v23
	v_and_b32_e32 v23, 0xffff0000, v23
	v_pk_fma_f32 v[30:31], v[48:49], v[8:9], v[30:31] neg_lo:[0,0,1] neg_hi:[0,0,1]
	v_pk_mul_f32 v[8:9], v[32:33], v[8:9]
	v_lshlrev_b32_e32 v18, 16, v19
	v_and_b32_e32 v19, 0xffff0000, v19
	v_pk_fma_f32 v[14:15], v[48:49], v[14:15], v[8:9]
	v_pk_mul_f32 v[8:9], v[32:33], v[22:23]
	v_pk_fma_f32 v[28:29], v[56:57], v[52:53], v[28:29]
	v_pk_fma_f32 v[8:9], v[48:49], v[18:19], v[8:9] neg_lo:[0,0,1] neg_hi:[0,0,1]
	v_lshlrev_b32_e32 v42, 16, v10
	v_pk_mul_f32 v[52:53], v[8:9], s[44:45] op_sel_hi:[1,0]
	v_pk_mul_f32 v[8:9], v[32:33], v[18:19]
	v_and_b32_e32 v43, 0xffff0000, v10
	v_pk_fma_f32 v[8:9], v[48:49], v[22:23], v[8:9]
	v_lshlrev_b32_e32 v46, 16, v16
	v_and_b32_e32 v47, 0xffff0000, v16
	v_lshlrev_b32_e32 v50, 16, v20
	v_and_b32_e32 v51, 0xffff0000, v20
	v_lshlrev_b32_e32 v54, 16, v24
	v_and_b32_e32 v55, 0xffff0000, v24
	v_pk_mul_f32 v[18:19], v[8:9], s[44:45] op_sel_hi:[1,0]
	v_mov_b32_e32 v9, v36
	v_mov_b32_e32 v36, v35
	v_mov_b32_e32 v8, v34
	v_pk_mul_f32 v[22:23], v[36:37], v[46:47]
	v_pk_mul_f32 v[32:33], v[36:37], v[42:43]
	v_pk_mul_f32 v[34:35], v[36:37], v[54:55]
	v_pk_mul_f32 v[36:37], v[36:37], v[50:51]
	v_pk_fma_f32 v[22:23], v[8:9], v[42:43], v[22:23] neg_lo:[0,0,1] neg_hi:[0,0,1]
	v_pk_fma_f32 v[32:33], v[8:9], v[46:47], v[32:33]
	v_pk_fma_f32 v[34:35], v[8:9], v[50:51], v[34:35] neg_lo:[0,0,1] neg_hi:[0,0,1]
	v_pk_fma_f32 v[8:9], v[8:9], v[54:55], v[36:37]
	v_lshlrev_b32_e32 v16, 16, v17
	v_and_b32_e32 v17, 0xffff0000, v17
	v_pk_mul_f32 v[36:37], v[8:9], s[44:45] op_sel_hi:[1,0]
	v_mov_b32_e32 v9, v40
	v_mov_b32_e32 v40, v39
	v_lshlrev_b32_e32 v10, 16, v11
	v_and_b32_e32 v11, 0xffff0000, v11
	v_mov_b32_e32 v8, v38
	v_pk_mul_f32 v[38:39], v[40:41], v[16:17]
	v_lshlrev_b32_e32 v24, 16, v25
	v_and_b32_e32 v25, 0xffff0000, v25
	v_pk_fma_f32 v[38:39], v[8:9], v[10:11], v[38:39] neg_lo:[0,0,1] neg_hi:[0,0,1]
	v_pk_mul_f32 v[10:11], v[40:41], v[10:11]
	v_lshlrev_b32_e32 v20, 16, v21
	v_and_b32_e32 v21, 0xffff0000, v21
	v_pk_fma_f32 v[16:17], v[8:9], v[16:17], v[10:11]
	v_pk_mul_f32 v[10:11], v[40:41], v[24:25]
	v_pk_mul_f32 v[44:45], v[44:45], s[44:45] op_sel_hi:[1,0]
	v_pk_fma_f32 v[10:11], v[8:9], v[20:21], v[10:11] neg_lo:[0,0,1] neg_hi:[0,0,1]
	v_pk_mul_f32 v[34:35], v[34:35], s[44:45] op_sel_hi:[1,0]
	v_pk_mul_f32 v[42:43], v[10:11], s[44:45] op_sel_hi:[1,0]
	v_pk_mul_f32 v[10:11], v[40:41], v[20:21]
	v_pk_mul_f32 v[28:29], v[28:29], s[44:45] op_sel_hi:[1,0]
	v_pk_fma_f32 v[8:9], v[8:9], v[24:25], v[10:11]
	v_cvt_pk_bf16_f32 v10, v22, v23
	v_pk_mul_f32 v[20:21], v[8:9], s[44:45] op_sel_hi:[1,0]
	v_cvt_pk_bf16_f32 v8, v26, v27
	v_cvt_pk_bf16_f32 v9, v30, v31
	v_cvt_pk_bf16_f32 v11, v38, v39
	ds_write_b128 v3, v[8:11]
	v_cvt_pk_bf16_f32 v8, v0, v1
	v_cvt_pk_bf16_f32 v9, v14, v15
	v_cvt_pk_bf16_f32 v10, v32, v33
	v_cvt_pk_bf16_f32 v11, v16, v17
	ds_write_b128 v3, v[8:11] offset:128
	v_cvt_pk_bf16_f32 v8, v44, v45
	v_cvt_pk_bf16_f32 v9, v52, v53
	v_cvt_pk_bf16_f32 v10, v34, v35
	v_cvt_pk_bf16_f32 v11, v42, v43
	ds_write_b128 v3, v[8:11] offset:17408
	v_cvt_pk_bf16_f32 v8, v28, v29
	v_cvt_pk_bf16_f32 v9, v18, v19
	v_cvt_pk_bf16_f32 v10, v36, v37
	v_cvt_pk_bf16_f32 v11, v20, v21
	ds_write_b128 v3, v[8:11] offset:17536
	v_bfe_u32 v9, v5, 4, 4
	v_add_u32_e32 v10, v68, v9
	v_and_b32_e32 v8, 0x78, v2
	v_mad_i64_i32 v[0:1], s[0:1], v10, s57, v[66:67]
	v_lshl_add_u64 v[0:1], v[0:1], 0, v[72:73]
	v_lshlrev_b32_e32 v64, 1, v8
	v_lshl_add_u64 v[0:1], v[0:1], 0, v[64:65]
	v_mul_u32_u24_e32 v8, 0x48, v8
	v_lshlrev_b32_e32 v11, 1, v8
	v_lshlrev_b32_e32 v9, 1, v9
	v_add_u32_e32 v14, v4, v11
	v_add3_u32 v13, v4, v9, v11
	v_add_u32_e32 v15, v14, v9
	v_add_u32_e32 v8, 32, v10
	v_mad_i64_i32 v[8:9], s[0:1], v8, s57, v[66:67]
	v_lshl_add_u64 v[8:9], v[8:9], 0, v[72:73]
	v_lshl_add_u64 v[8:9], v[8:9], 0, v[64:65]
	v_and_b32_e32 v20, 15, v5
	v_bfe_u32 v21, v5, 4, 2
	v_lshrrev_b32_e32 v5, 2, v5
	v_and_or_b32 v76, v5, 48, v20
	v_lshlrev_b32_e32 v5, 2, v21
	v_lshlrev_b32_e32 v74, 4, v21
	v_sub_u32_e32 v69, v76, v5
	v_add_u32_e32 v16, -2, v69
	v_cvt_f32_i32_e32 v16, v16
	v_add_u32_e32 v17, -3, v69
	v_subrev_u32_e32 v22, 17, v69
	v_subrev_u32_e32 v23, 18, v69
	v_subrev_u32_e32 v24, 19, v69
	v_subrev_u32_e32 v25, 33, v69
	v_cvt_f32_i32_e32 v17, v17
	v_cvt_f32_i32_e32 v22, v22
	v_cvt_f32_i32_e32 v23, v23
	v_cvt_f32_i32_e32 v24, v24
	v_cvt_f32_i32_e32 v25, v25
	v_subrev_u32_e32 v26, 34, v69
	v_subrev_u32_e32 v27, 35, v69
	v_cvt_f32_i32_e32 v26, v26
	v_cvt_f32_i32_e32 v34, v27
	v_subrev_u32_e32 v28, 49, v69
	s_add_i32 s45, s45, s48
	s_cmpk_gt_i32 s2, 0x62f
	s_waitcnt vmcnt(3) lgkmcnt(0)
	v_mov_b64_e32 v[0:1], v[192:193]
	v_mov_b64_e32 v[2:3], v[194:195]
	ds_write_b16 v13, v0 offset:34816
	ds_write_b16_d16_hi v15, v0 offset:34960
	ds_write_b16 v13, v1 offset:35104
	ds_write_b16_d16_hi v15, v1 offset:35248
	ds_write_b16 v13, v2 offset:35392
	ds_write_b16_d16_hi v15, v2 offset:35536
	ds_write_b16 v13, v3 offset:35680
	ds_write_b16_d16_hi v15, v3 offset:35824
	v_add_u32_e32 v0, v68, v7
	v_mad_i64_i32 v[0:1], s[0:1], v0, s57, v[66:67]
	v_lshl_add_u64 v[0:1], v[0:1], 0, v[72:73]
	v_lshl_add_u64 v[0:1], v[0:1], 0, v[64:65]
	v_lshlrev_b32_e32 v7, 1, v7
	v_add3_u32 v11, v4, v7, v11
	v_add_u32_e32 v7, v14, v7
	s_waitcnt vmcnt(2) lgkmcnt(0)
	v_mov_b64_e32 v[0:1], v[196:197]
	v_mov_b64_e32 v[2:3], v[198:199]
	ds_write_b16 v11, v0 offset:34816
	ds_write_b16_d16_hi v7, v0 offset:34960
	ds_write_b16 v11, v1 offset:35104
	ds_write_b16_d16_hi v7, v1 offset:35248
	ds_write_b16 v11, v2 offset:35392
	ds_write_b16_d16_hi v7, v2 offset:35536
	ds_write_b16 v11, v3 offset:35680
	ds_write_b16_d16_hi v7, v3 offset:35824
	v_cvt_f32_i32_e32 v8, v6
	v_add_u32_e32 v6, 48, v10
	v_mad_i64_i32 v[6:7], s[0:1], v6, s57, v[66:67]
	v_lshl_add_u64 v[6:7], v[6:7], 0, v[72:73]
	v_lshl_add_u64 v[6:7], v[6:7], 0, v[64:65]
	s_waitcnt vmcnt(1) lgkmcnt(0)
	v_mov_b64_e32 v[0:1], v[200:201]
	v_mov_b64_e32 v[2:3], v[202:203]
	ds_write_b16 v13, v0 offset:34880
	ds_write_b16_d16_hi v15, v0 offset:35024
	ds_write_b16 v13, v1 offset:35168
	ds_write_b16_d16_hi v15, v1 offset:35312
	ds_write_b16 v13, v2 offset:35456
	ds_write_b16_d16_hi v15, v2 offset:35600
	ds_write_b16 v13, v3 offset:35744
	ds_write_b16_d16_hi v15, v3 offset:35888
	v_sub_f32_e32 v8, 0xc0a00000, v8
	v_cmp_gt_f32_e32 vcc, s53, v8
	v_add_u32_e32 v9, v4, v74
	v_xad_u32 v10, v5, -1, v76
	v_cndmask_b32_e32 v29, 0, v78, vcc
	v_add_f32_e32 v8, v8, v29
	v_exp_f32_e32 v6, v8
	v_cndmask_b32_e32 v7, 0, v79, vcc
	v_mad_u32_u24 v18, v76, s62, v9
	v_mad_u32_u24 v19, v20, s62, v9
	v_ldexp_f32 v6, v6, v7
	v_sub_f32_e32 v6, 1.0, v6
	v_cmp_gt_f32_e32 vcc, s54, v6
	v_cvt_f32_i32_e32 v9, v69
	v_cvt_f32_i32_e32 v10, v10
	v_cndmask_b32_e64 v7, 0, 32, vcc
	v_ldexp_f32 v6, v6, v7
	v_log_f32_e32 v6, v6
	v_cndmask_b32_e32 v7, 0, v80, vcc
	v_or_b32_e32 v14, 32, v5
	s_waitcnt vmcnt(0) lgkmcnt(0)
	v_mov_b64_e32 v[0:1], v[204:205]
	v_mov_b64_e32 v[2:3], v[206:207]
	ds_write_b16 v13, v0 offset:34912
	ds_write_b16_d16_hi v15, v0 offset:35056
	ds_write_b16 v13, v1 offset:35200
	ds_write_b16_d16_hi v15, v1 offset:35344
	ds_write_b16 v13, v2 offset:35488
	ds_write_b16_d16_hi v15, v2 offset:35632
	ds_write_b16 v13, v3 offset:35776
	ds_write_b16_d16_hi v15, v3 offset:35920
	v_mul_f32_e32 v8, 0x3f317217, v6
	v_fma_f32 v8, v6, s55, -v8
	v_fmac_f32_e32 v8, 0x3377d1cf, v6
	v_fmac_f32_e32 v8, 0x3f317217, v6
	v_cmp_lt_f32_e64 vcc, |v6|, s56
	s_waitcnt lgkmcnt(0)
	s_barrier
	v_cndmask_b32_e32 v6, v6, v8, vcc
	v_sub_f32_e32 v6, v6, v7
	ds_read_b128 v[0:3], v19 offset:17408
	v_sub_u32_e32 v14, v76, v14
	v_mul_f32_e32 v83, 0x3fb8aa3b, v6
	v_cvt_f32_i32_e32 v14, v14
	v_mul_f32_e64 v6, |v9|, v83
	v_mul_f32_e64 v7, |v10|, v83
	v_mul_f32_e64 v8, |v16|, v83
	v_cmp_gt_f32_e32 vcc, s53, v6
	v_cmp_gt_f32_e64 s[0:1], s53, v7
	v_cmp_gt_f32_e64 s[4:5], s53, v8
	v_or_b32_e32 v11, 16, v5
	v_or_b32_e32 v5, 48, v5
	v_cndmask_b32_e32 v6, 0, v78, vcc
	v_cndmask_b32_e64 v7, 0, v78, s[0:1]
	v_cndmask_b32_e64 v8, 0, v78, s[4:5]
	v_sub_u32_e32 v11, v76, v11
	v_sub_u32_e32 v5, v76, v5
	v_fma_f32 v42, |v9|, v83, v6
	v_fma_f32 v10, |v10|, v83, v7
	v_fma_f32 v43, |v16|, v83, v8
	ds_read_b128 v[56:59], v18
	ds_read_b128 v[6:9], v19 offset:21760
	v_cvt_f32_i32_e32 v11, v11
	v_cvt_f32_i32_e32 v5, v5
	v_mul_f32_e64 v27, |v17|, v83
	v_mul_f32_e64 v29, |v22|, v83
	v_mul_f32_e64 v30, |v23|, v83
	v_mul_f32_e64 v31, |v24|, v83
	v_mul_f32_e64 v32, |v14|, v83
	v_mul_f32_e64 v33, |v25|, v83
	v_cmp_gt_f32_e64 s[6:7], s53, v27
	v_cmp_gt_f32_e64 s[10:11], s53, v29
	v_cmp_gt_f32_e64 s[12:13], s53, v30
	v_cmp_gt_f32_e64 s[14:15], s53, v31
	v_cmp_gt_f32_e64 s[16:17], s53, v32
	v_cmp_gt_f32_e64 s[18:19], s53, v33
	v_cndmask_b32_e64 v27, 0, v78, s[6:7]
	v_cndmask_b32_e64 v29, 0, v78, s[10:11]
	v_cndmask_b32_e64 v30, 0, v78, s[12:13]
	v_cndmask_b32_e64 v31, 0, v78, s[14:15]
	v_cndmask_b32_e64 v32, 0, v78, s[16:17]
	v_cndmask_b32_e64 v33, 0, v78, s[18:19]
	v_fma_f32 v44, |v17|, v83, v27
	v_fma_f32 v45, |v22|, v83, v29
	v_fma_f32 v48, |v23|, v83, v30
	v_fma_f32 v49, |v24|, v83, v31
	v_fma_f32 v50, |v14|, v83, v32
	v_fma_f32 v13, |v25|, v83, v33
	ds_read_b128 v[60:63], v18 offset:64
	ds_read_b128 v[14:17], v19 offset:17472
	ds_read_b128 v[22:25], v19 offset:26112
	s_waitcnt lgkmcnt(4)
	v_mfma_f32_16x16x32_bf16 v[0:3], v[0:3], v[56:59], 0
	v_cvt_f32_i32_e32 v64, v28
	v_mul_f32_e64 v28, |v11|, v83
	v_mul_f32_e64 v35, |v26|, v83
	v_mul_f32_e64 v36, |v34|, v83
	v_mul_f32_e64 v37, |v5|, v83
	v_cmp_gt_f32_e64 s[8:9], s53, v28
	v_cmp_gt_f32_e64 s[20:21], s53, v35
	v_cmp_gt_f32_e64 s[22:23], s53, v36
	v_cmp_gt_f32_e64 s[24:25], s53, v37
	v_cndmask_b32_e64 v28, 0, v78, s[8:9]
	v_cndmask_b32_e64 v35, 0, v78, s[20:21]
	v_cndmask_b32_e64 v36, 0, v78, s[22:23]
	v_cndmask_b32_e64 v38, 0, v78, s[24:25]
	v_fma_f32 v11, |v11|, v83, v28
	v_fma_f32 v91, |v26|, v83, v35
	ds_read_b128 v[26:29], v19 offset:21824
	ds_read_b128 v[30:33], v19 offset:30464
	v_fma_f32 v93, |v34|, v83, v36
	ds_read_b128 v[34:37], v19 offset:26176
	v_fma_f32 v5, |v5|, v83, v38
	ds_read_b128 v[38:41], v19 offset:30528
	s_waitcnt lgkmcnt(5)
	v_mfma_f32_16x16x32_bf16 v[0:3], v[14:17], v[60:63], v[0:3]
	ds_read_b128 v[14:17], v19 offset:17536
	v_exp_f32_e32 v102, v48
	v_exp_f32_e32 v103, v49
	v_mfma_f32_16x16x32_bf16 v[6:9], v[6:9], v[56:59], 0
	v_exp_f32_e32 v104, v50
	v_exp_f32_e32 v96, v42
	v_exp_f32_e32 v97, v10
	s_waitcnt lgkmcnt(5)
	v_mfma_f32_16x16x32_bf16 v[22:25], v[22:25], v[56:59], 0
	v_exp_f32_e32 v98, v43
	v_exp_f32_e32 v99, v44
	v_exp_f32_e32 v101, v45
	s_waitcnt lgkmcnt(3)
	v_mfma_f32_16x16x32_bf16 v[30:33], v[30:33], v[56:59], 0
	v_mul_f32_e64 v75, |v64|, v83
	v_cndmask_b32_e32 v46, 0, v79, vcc
	v_cndmask_b32_e64 v47, 0, v79, s[0:1]
	v_mfma_f32_16x16x32_bf16 v[6:9], v[26:29], v[60:63], v[6:9]
	ds_read_b128 v[52:55], v18 offset:128
	ds_read_b128 v[26:29], v19 offset:21888
	v_exp_f32_e32 v100, v11
	v_ldexp_f32 v10, v96, v46
	s_waitcnt lgkmcnt(4)
	v_mfma_f32_16x16x32_bf16 v[22:25], v[34:37], v[60:63], v[22:25]
	v_ldexp_f32 v11, v97, v47
	v_cmp_gt_f32_e32 vcc, s53, v75
	v_cndmask_b32_e64 v77, 0, v79, s[4:5]
	s_waitcnt lgkmcnt(3)
	v_mfma_f32_16x16x32_bf16 v[30:33], v[38:41], v[60:63], v[30:33]
	ds_read_b128 v[48:51], v18 offset:192
	ds_read_b128 v[34:37], v19 offset:17600
	ds_read_b128 v[38:41], v19 offset:26240
	v_cndmask_b32_e64 v84, 0, v79, s[6:7]
	v_ldexp_f32 v18, v98, v77
	s_waitcnt lgkmcnt(4)
	v_mfma_f32_16x16x32_bf16 v[0:3], v[14:17], v[52:55], v[0:3]
	ds_read_b128 v[14:17], v19 offset:21952
	ds_read_b128 v[42:45], v19 offset:30592
	v_exp_f32_e32 v13, v13
	v_exp_f32_e32 v91, v91
	s_waitcnt lgkmcnt(3)
	v_mfma_f32_16x16x32_bf16 v[0:3], v[34:37], v[48:51], v[0:3]
	v_exp_f32_e32 v93, v93
	v_cndmask_b32_e64 v90, 0, v79, s[18:19]
	v_cndmask_b32_e64 v89, 0, v79, s[16:17]
	v_mfma_f32_16x16x32_bf16 v[6:9], v[26:29], v[52:55], v[6:9]
	ds_read_b128 v[26:29], v19 offset:26304
	s_nop 2
	v_pk_mul_f32 v[10:11], v[10:11], v[0:1]
	v_cndmask_b32_e32 v0, 0, v78, vcc
	v_fma_f32 v0, |v64|, v83, v0
	v_subrev_u32_e32 v1, 50, v69
	s_waitcnt lgkmcnt(3)
	v_mfma_f32_16x16x32_bf16 v[22:25], v[38:41], v[52:55], v[22:25]
	v_exp_f32_e32 v0, v0
	v_cvt_f32_i32_e32 v1, v1
	ds_read_b128 v[38:41], v19 offset:30656
	v_ldexp_f32 v19, v99, v84
	v_pk_mul_f32 v[18:19], v[18:19], v[2:3]
	v_cndmask_b32_e32 v2, 0, v79, vcc
	s_waitcnt lgkmcnt(3)
	v_mfma_f32_16x16x32_bf16 v[6:9], v[14:17], v[48:51], v[6:9]
	v_lshlrev_b32_e32 v64, 3, v21
	v_cndmask_b32_e64 v92, 0, v79, s[20:21]
	v_cndmask_b32_e64 v94, 0, v79, s[22:23]
	s_waitcnt lgkmcnt(1)
	v_mfma_f32_16x16x32_bf16 v[14:17], v[26:29], v[48:51], v[22:25]
	v_ldexp_f32 v29, v0, v2
	v_mul_f32_e64 v0, |v1|, v83
	v_cmp_gt_f32_e32 vcc, s53, v0
	v_mfma_f32_16x16x32_bf16 v[30:33], v[42:45], v[52:55], v[30:33]
	v_ldexp_f32 v43, v13, v90
	v_cndmask_b32_e32 v0, 0, v78, vcc
	v_fma_f32 v13, |v1|, v83, v0
	v_mul_u32_u24_e32 v0, 0x90, v20
	v_add3_u32 v21, v4, v64, v0
	v_exp_f32_e32 v5, v5
	v_ldexp_f32 v42, v104, v89
	v_ldexp_f32 v26, v91, v92
	v_ldexp_f32 v27, v93, v94
	v_add_u32_e32 v92, 0x9800, v21
	v_pk_mul_f32 v[46:47], v[42:43], v[14:15]
	v_pk_mul_f32 v[90:91], v[26:27], v[16:17]
	ds_read2_b64 v[14:17], v92 offset0:64 offset1:68
	v_exp_f32_e32 v13, v13
	v_cndmask_b32_e64 v95, 0, v79, s[24:25]
	v_ldexp_f32 v28, v5, v95
	v_cvt_pk_bf16_f32 v5, v18, v19
	v_cndmask_b32_e32 v18, 0, v79, vcc
	v_ldexp_f32 v18, v13, v18
	v_subrev_u32_e32 v13, 51, v69
	v_cndmask_b32_e64 v85, 0, v79, s[8:9]
	v_cndmask_b32_e64 v86, 0, v79, s[10:11]
	v_cndmask_b32_e64 v87, 0, v79, s[12:13]
	v_cndmask_b32_e64 v88, 0, v79, s[14:15]
	s_waitcnt lgkmcnt(1)
	v_mfma_f32_16x16x32_bf16 v[22:25], v[38:41], v[48:51], v[30:33]
	v_cvt_f32_i32_e32 v13, v13
	v_ldexp_f32 v34, v100, v85
	v_ldexp_f32 v35, v101, v86
	v_ldexp_f32 v36, v102, v87
	v_ldexp_f32 v37, v103, v88
	v_pk_mul_f32 v[6:7], v[34:35], v[6:7]
	v_pk_mul_f32 v[30:31], v[36:37], v[8:9]
	v_add_u32_e32 v75, 0x8800, v21
	v_cvt_pk_bf16_f32 v4, v10, v11
	v_add_u32_e32 v77, 0x9000, v21
	v_cvt_pk_bf16_f32 v6, v6, v7
	v_cvt_pk_bf16_f32 v7, v30, v31
	v_add_u32_e32 v93, 0xa000, v21
	v_add_u32_e32 v94, 0xa800, v21
	v_add_u32_e32 v69, 0xb000, v21
	v_add_u32_e32 v95, 0xb800, v21
	v_add_u32_e32 v96, 0xc000, v21
	v_pk_mul_f32 v[22:23], v[28:29], v[22:23]
	ds_read2_b64 v[0:3], v75 offset1:4
	ds_read2_b64 v[8:11], v77 offset0:32 offset1:36
	ds_read2_b64 v[26:29], v93 offset0:96 offset1:100
	ds_read2_b64 v[30:33], v94 offset0:128 offset1:132
	s_waitcnt lgkmcnt(4)
	v_mfma_f32_16x16x32_bf16 v[34:37], v[14:17], v[4:7], 0
	ds_read2_b64 v[14:17], v69 offset0:160 offset1:164
	v_mul_f32_e64 v19, |v13|, v83
	ds_read2_b64 v[38:41], v95 offset0:192 offset1:196
	ds_read2_b64 v[42:45], v96 offset0:224 offset1:228
	v_cmp_gt_f32_e32 vcc, s53, v19
	s_waitcnt lgkmcnt(6)
	v_mfma_f32_16x16x32_bf16 v[0:3], v[0:3], v[4:7], 0
	v_cvt_pk_bf16_f32 v89, v90, v91
	v_cndmask_b32_e32 v19, 0, v78, vcc
	v_fma_f32 v13, |v13|, v83, v19
	v_exp_f32_e32 v13, v13
	v_cndmask_b32_e32 v19, 0, v79, vcc
	s_waitcnt lgkmcnt(5)
	v_mfma_f32_16x16x32_bf16 v[8:11], v[8:11], v[4:7], 0
	v_cvt_pk_bf16_f32 v90, v22, v23
	v_ldexp_f32 v19, v13, v19
	v_pk_mul_f32 v[18:19], v[18:19], v[24:25]
	s_waitcnt lgkmcnt(4)
	v_mfma_f32_16x16x32_bf16 v[26:29], v[26:29], v[4:7], 0
	ds_read2_b64 v[22:25], v92 offset0:72 offset1:76
	v_cvt_pk_bf16_f32 v88, v46, v47
	v_cvt_pk_bf16_f32 v91, v18, v19
	s_waitcnt lgkmcnt(4)
	v_mfma_f32_16x16x32_bf16 v[30:33], v[30:33], v[4:7], 0
	v_ashrrev_i32_e32 v13, 31, v12
	v_lshlrev_b64 v[12:13], 15, v[12:13]
	v_lshlrev_b32_e32 v20, 8, v20
	s_waitcnt lgkmcnt(3)
	v_mfma_f32_16x16x32_bf16 v[84:87], v[14:17], v[4:7], 0
	ds_read2_b64 v[14:17], v75 offset0:8 offset1:12
	v_mov_b32_e32 v75, v65
	v_mov_b32_e32 v21, v65
	s_waitcnt lgkmcnt(3)
	v_mfma_f32_16x16x32_bf16 v[38:41], v[38:41], v[4:7], 0
	v_readlane_b32 s4, v255, 2
	v_readlane_b32 s6, v255, 4
	v_readlane_b32 s7, v255, 5
	s_waitcnt lgkmcnt(2)
	v_mfma_f32_16x16x32_bf16 v[42:45], v[42:45], v[4:7], 0
	ds_read2_b64 v[4:7], v77 offset0:40 offset1:44
	v_mov_b32_e32 v77, v65
	v_readlane_b32 s5, v255, 3
	s_waitcnt lgkmcnt(1)
	v_mfma_f32_16x16x32_bf16 v[16:19], v[14:17], v[88:91], v[0:3]
	v_readlane_b32 s8, v255, 6
	v_readlane_b32 s9, v255, 7
	v_readlane_b32 s10, v255, 8
	s_waitcnt lgkmcnt(0)
	v_mfma_f32_16x16x32_bf16 v[0:3], v[4:7], v[88:91], v[8:11]
	v_readlane_b32 s11, v255, 9
	s_nop 1
	ds_read2_b64 v[8:11], v93 offset0:104 offset1:108
	v_readlane_b32 s12, v255, 10
	v_mfma_f32_16x16x32_bf16 v[4:7], v[22:25], v[88:91], v[34:37]
	ds_read2_b64 v[22:25], v94 offset0:136 offset1:140
	v_readlane_b32 s13, v255, 11
	v_readlane_b32 s14, v255, 12
	s_waitcnt lgkmcnt(1)
	v_mfma_f32_16x16x32_bf16 v[8:11], v[8:11], v[88:91], v[26:29]
	s_nop 2
	v_lshl_add_u64 v[26:27], s[42:43], 0, v[12:13]
	v_lshl_add_u64 v[26:27], v[26:27], 0, v[74:75]
	v_lshl_add_u64 v[108:109], v[26:27], 0, v[20:21]
	s_waitcnt lgkmcnt(0)
	v_mfma_f32_16x16x32_bf16 v[12:15], v[22:25], v[88:91], v[30:33]
	ds_read2_b64 v[22:25], v69 offset0:168 offset1:172
	v_add_co_u32_e32 v134, vcc, s63, v108
	s_nop 1
	v_addc_co_u32_e32 v135, vcc, 0, v109, vcc
	v_add_co_u32_e32 v136, vcc, s64, v108
	s_nop 1
	v_addc_co_u32_e32 v137, vcc, 0, v109, vcc
	v_add_co_u32_e32 v138, vcc, s65, v108
	s_nop 1
	v_addc_co_u32_e32 v139, vcc, 0, v109, vcc
	v_add_co_u32_e32 v140, vcc, s66, v108
	s_nop 1
	v_addc_co_u32_e32 v141, vcc, 0, v109, vcc
	v_add_co_u32_e32 v142, vcc, s67, v108
	s_nop 1
	v_addc_co_u32_e32 v143, vcc, 0, v109, vcc
	v_add_co_u32_e32 v150, vcc, s68, v108
	s_nop 1
	v_addc_co_u32_e32 v151, vcc, 0, v109, vcc
	v_add_co_u32_e32 v152, vcc, s69, v108
	s_nop 1
	v_addc_co_u32_e32 v153, vcc, 0, v109, vcc
	global_load_dwordx4 v[160:163], v[108:109], off
	global_load_dwordx4 v[164:167], v[108:109], off offset:64
	global_load_dwordx4 v[168:171], v[108:109], off offset:128
	global_load_dwordx4 v[172:175], v[108:109], off offset:192
	global_load_dwordx4 v[176:179], v[134:135], off
	global_load_dwordx4 v[180:183], v[134:135], off offset:64
	global_load_dwordx4 v[184:187], v[134:135], off offset:128
	global_load_dwordx4 v[188:191], v[134:135], off offset:192
	global_load_dwordx4 v[192:195], v[136:137], off
	global_load_dwordx4 v[196:199], v[136:137], off offset:64
	global_load_dwordx4 v[200:203], v[136:137], off offset:128
	global_load_dwordx4 v[204:207], v[136:137], off offset:192
	global_load_dwordx4 v[208:211], v[138:139], off
	global_load_dwordx4 v[212:215], v[138:139], off offset:64
	global_load_dwordx4 v[216:219], v[138:139], off offset:128
	global_load_dwordx4 v[220:223], v[138:139], off offset:192
	global_load_dwordx4 v[224:227], v[140:141], off
	global_load_dwordx4 v[228:231], v[140:141], off offset:64
	global_load_dwordx4 v[232:235], v[140:141], off offset:128
	global_load_dwordx4 v[236:239], v[140:141], off offset:192
	global_load_dwordx4 v[240:243], v[142:143], off
	global_load_dwordx4 v[244:247], v[142:143], off offset:64
	global_load_dwordx4 v[248:251], v[142:143], off offset:128
	ds_read2_b64 v[30:33], v95 offset0:200 offset1:204
	s_waitcnt lgkmcnt(0)
	v_mfma_f32_16x16x32_bf16 v[20:23], v[22:25], v[88:91], v[84:87]
	v_ashrrev_i32_e32 v69, 31, v68
	v_mfma_f32_16x16x32_bf16 v[84:87], v[30:33], v[88:91], v[38:41]
	ds_read2_b64 v[30:33], v96 offset0:232 offset1:236
	s_waitcnt lgkmcnt(0)
	v_mfma_f32_16x16x32_bf16 v[88:91], v[30:33], v[88:91], v[42:45]
	s_nop 0
	s_waitcnt lgkmcnt(0)
	global_load_dwordx4 v[96:99], v[142:143], off offset:192
	global_load_dwordx4 v[100:103], v[150:151], off
	global_load_dwordx4 v[104:107], v[150:151], off offset:64
	s_waitcnt vmcnt(22)
	v_mfma_f32_16x16x32_bf16 v[36:39], v[160:163], v[56:59], 0
	v_mfma_f32_16x16x32_bf16 v[36:39], v[164:167], v[60:63], v[36:39]
	v_mfma_f32_16x16x32_bf16 v[36:39], v[168:171], v[52:55], v[36:39]
	v_mfma_f32_16x16x32_bf16 v[36:39], v[172:175], v[48:51], v[36:39]
	global_load_dwordx4 v[160:163], v[150:151], off offset:128
	global_load_dwordx4 v[164:167], v[150:151], off offset:192
	global_load_dwordx4 v[168:171], v[152:153], off
	global_load_dwordx4 v[172:175], v[152:153], off offset:64
	s_waitcnt vmcnt(22)
	v_mfma_f32_16x16x32_bf16 v[24:27], v[176:179], v[56:59], 0
	v_mfma_f32_16x16x32_bf16 v[24:27], v[180:183], v[60:63], v[24:27]
	v_mfma_f32_16x16x32_bf16 v[24:27], v[184:187], v[52:55], v[24:27]
	v_mfma_f32_16x16x32_bf16 v[24:27], v[188:191], v[48:51], v[24:27]
	global_load_dwordx4 v[176:179], v[152:153], off offset:128
	global_load_dwordx4 v[180:183], v[152:153], off offset:192
	s_waitcnt vmcnt(20)
	v_mfma_f32_16x16x32_bf16 v[28:31], v[192:195], v[56:59], 0
	v_mfma_f32_16x16x32_bf16 v[28:31], v[196:199], v[60:63], v[28:31]
	v_mfma_f32_16x16x32_bf16 v[28:31], v[200:203], v[52:55], v[28:31]
	v_mfma_f32_16x16x32_bf16 v[28:31], v[204:207], v[48:51], v[28:31]
	s_waitcnt vmcnt(16)
	v_mfma_f32_16x16x32_bf16 v[32:35], v[208:211], v[56:59], 0
	v_mfma_f32_16x16x32_bf16 v[32:35], v[212:215], v[60:63], v[32:35]
	v_mfma_f32_16x16x32_bf16 v[32:35], v[216:219], v[52:55], v[32:35]
	v_mfma_f32_16x16x32_bf16 v[32:35], v[220:223], v[48:51], v[32:35]
	s_waitcnt vmcnt(12)
	v_mfma_f32_16x16x32_bf16 v[40:43], v[224:227], v[56:59], 0
	v_mfma_f32_16x16x32_bf16 v[40:43], v[228:231], v[60:63], v[40:43]
	v_mfma_f32_16x16x32_bf16 v[40:43], v[232:235], v[52:55], v[40:43]
	v_mfma_f32_16x16x32_bf16 v[40:43], v[236:239], v[48:51], v[40:43]
	s_waitcnt vmcnt(8)
	v_mfma_f32_16x16x32_bf16 v[44:47], v[240:243], v[56:59], 0
	v_mfma_f32_16x16x32_bf16 v[44:47], v[244:247], v[60:63], v[44:47]
	v_mfma_f32_16x16x32_bf16 v[44:47], v[248:251], v[52:55], v[44:47]
	v_mfma_f32_16x16x32_bf16 v[44:47], v[96:99], v[48:51], v[44:47]
	s_waitcnt vmcnt(4)
	v_mfma_f32_16x16x32_bf16 v[92:95], v[100:103], v[56:59], 0
	v_mfma_f32_16x16x32_bf16 v[92:95], v[104:107], v[60:63], v[92:95]
	v_mfma_f32_16x16x32_bf16 v[92:95], v[160:163], v[52:55], v[92:95]
	v_mfma_f32_16x16x32_bf16 v[92:95], v[164:167], v[48:51], v[92:95]
	s_waitcnt vmcnt(0)
	v_mfma_f32_16x16x32_bf16 v[56:59], v[168:171], v[56:59], 0
	v_mfma_f32_16x16x32_bf16 v[56:59], v[172:175], v[60:63], v[56:59]
	v_mfma_f32_16x16x32_bf16 v[52:55], v[176:179], v[52:55], v[56:59]
	v_mfma_f32_16x16x32_bf16 v[48:51], v[180:183], v[48:51], v[52:55]
	v_readlane_b32 s15, v255, 13
	v_readlane_b32 s16, v255, 14
	v_readlane_b32 s17, v255, 15
	v_readlane_b32 s18, v255, 16
	v_readlane_b32 s19, v255, 17
	s_waitcnt lgkmcnt(0)
	s_nop 5
	s_waitcnt lgkmcnt(0)
	s_nop 2
	s_nop 2
	s_waitcnt lgkmcnt(0)
	s_nop 0
	s_nop 3
	s_waitcnt lgkmcnt(0)
	s_waitcnt lgkmcnt(0)
	s_waitcnt lgkmcnt(0)
	s_nop 0
	s_waitcnt lgkmcnt(0)
	s_nop 0
	s_waitcnt lgkmcnt(0)
	s_waitcnt lgkmcnt(0)
	s_nop 0
	s_waitcnt lgkmcnt(0)
	v_lshl_add_u64 v[100:101], v[68:69], 0, v[76:77]
	v_mad_u64_u32 v[60:61], s[0:1], v100, s57, v[66:67]
	v_mad_i32_i24 v61, v101, s57, v61
	v_lshl_add_u64 v[60:61], v[60:61], 0, v[72:73]
	v_lshl_add_u64 v[102:103], v[60:61], 0, v[64:65]
	v_add_co_u32_e32 v60, vcc, s63, v102
	s_waitcnt lgkmcnt(0)
	v_addc_co_u32_e32 v61, vcc, 0, v103, vcc
	global_load_dwordx2 v[68:69], v[60:61], off offset:512
	v_lshl_add_u64 v[232:233], v[102:103], 0, s[46:47]
	v_lshl_add_u64 v[234:235], v[70:71], 2, s[6:7]
	v_lshl_add_u64 v[234:235], v[234:235], 0, v[74:75]
	global_load_dwordx2 v[186:187], v[232:233], off offset:32
	global_load_dwordx2 v[188:189], v[232:233], off offset:64
	global_load_dwordx2 v[190:191], v[232:233], off offset:96
	global_load_dwordx2 v[192:193], v[232:233], off offset:128
	global_load_dwordx2 v[194:195], v[232:233], off offset:160
	global_load_dwordx2 v[196:197], v[232:233], off offset:192
	global_load_dwordx2 v[198:199], v[232:233], off offset:224
	global_load_dwordx4 v[204:207], v[234:235], off offset:64
	global_load_dwordx4 v[208:211], v[234:235], off offset:128
	global_load_dwordx4 v[212:215], v[234:235], off offset:192
	global_load_dwordx4 v[216:219], v[234:235], off offset:256
	global_load_dwordx4 v[220:223], v[234:235], off offset:320
	global_load_dwordx4 v[224:227], v[234:235], off offset:384
	global_load_dwordx4 v[228:231], v[234:235], off offset:448
	s_nop 0
	v_add_u32_e32 v56, 1, v76
	v_cvt_f32_ubyte0_e32 v56, v56
	v_mul_f32_e32 v57, v83, v56
	v_cmp_gt_f32_e32 vcc, s53, v57
	s_waitcnt vmcnt(0) lgkmcnt(0)
	v_lshlrev_b32_e32 v77, 16, v68
	v_cndmask_b32_e32 v57, 0, v78, vcc
	v_fmac_f32_e32 v57, v83, v56
	v_exp_f32_e32 v56, v57
	v_cndmask_b32_e32 v52, 0, v79, vcc
	v_and_b32_e32 v68, 0xffff0000, v68
	v_cmp_lt_i32_e32 vcc, v157, v156
	v_ldexp_f32 v62, v56, v52
	v_pk_fma_f32 v[58:59], v[62:63], v[50:51], v[90:91] op_sel_hi:[0,1,1]
	v_lshlrev_b64 v[50:51], 11, v[100:101]
	v_lshl_add_u64 v[50:51], s[30:31], 0, v[50:51]
	v_lshl_add_u64 v[52:53], v[50:51], 0, v[72:73]
	v_mul_f32_e32 v72, 0xbfb8aa3b, v77
	v_pk_fma_f32 v[54:55], v[62:63], v[92:93], v[84:85] op_sel_hi:[0,1,1]
	v_exp_f32_e32 v84, v72
	v_mul_f32_e32 v72, 0xbfb8aa3b, v68
	v_exp_f32_e32 v85, v72
	v_pk_fma_f32 v[60:61], v[62:63], v[48:49], v[88:89] op_sel_hi:[0,1,1]
	v_cndmask_b32_e32 v48, v155, v157, vcc
	v_cmp_lt_i32_e32 vcc, v158, v156
	v_lshlrev_b32_e32 v76, 2, v48
	v_pk_fma_f32 v[56:57], v[62:63], v[94:95], v[86:87] op_sel_hi:[0,1,1]
	v_cndmask_b32_e32 v48, v155, v158, vcc
	v_lshlrev_b32_e32 v63, 2, v48
	v_pk_fma_f32 v[18:19], v[62:63], v[38:39], v[18:19] op_sel_hi:[0,1,1]
	v_pk_add_f32 v[38:39], v[84:85], 1.0 op_sel_hi:[1,0]
	v_lshlrev_b32_e32 v83, 16, v69
	v_and_b32_e32 v86, 0xffff0000, v69
	v_div_scale_f32 v69, s[0:1], v39, v39, v68
	v_rcp_f32_e32 v84, v69
	v_pk_fma_f32 v[16:17], v[62:63], v[36:37], v[16:17] op_sel_hi:[0,1,1]
	v_add_f32_e32 v36, 0, v16
	v_add_f32_e32 v85, v17, v36
	v_fma_f32 v36, -v69, v84, 1.0
	v_fmac_f32_e32 v84, v36, v84
	v_div_scale_f32 v36, vcc, v68, v39, v68
	v_mul_f32_e32 v37, v36, v84
	v_fma_f32 v87, -v69, v37, v36
	v_fmac_f32_e32 v37, v87, v84
	v_div_scale_f32 v87, s[0:1], v38, v38, v77
	v_rcp_f32_e32 v88, v87
	v_fma_f32 v36, -v69, v37, v36
	v_div_fmas_f32 v36, v36, v84, v37
	v_div_fixup_f32 v37, v36, v39, v68
	v_fma_f32 v36, -v87, v88, 1.0
	v_fmac_f32_e32 v88, v36, v88
	v_div_scale_f32 v36, vcc, v77, v38, v77
	v_mul_f32_e32 v39, v36, v88
	v_fma_f32 v68, -v87, v39, v36
	v_fmac_f32_e32 v39, v68, v88
	v_fma_f32 v36, -v87, v39, v36
	v_div_fmas_f32 v36, v36, v88, v39
	v_div_fixup_f32 v36, v36, v38, v77
	v_add_f32_e32 v38, v18, v85
	v_add_f32_e32 v38, v19, v38
	v_pk_fma_f32 v[0:1], v[62:63], v[24:25], v[0:1] op_sel_hi:[0,1,1]
	v_add_f32_e32 v24, v38, v0
	v_pk_fma_f32 v[2:3], v[62:63], v[26:27], v[2:3] op_sel_hi:[0,1,1]
	v_add_f32_e32 v24, v1, v24
	v_add_f32_e32 v24, v2, v24
	v_add_f32_e32 v24, v3, v24
	v_pk_fma_f32 v[4:5], v[62:63], v[28:29], v[4:5] op_sel_hi:[0,1,1]
	v_add_f32_e32 v24, v24, v4
	v_pk_fma_f32 v[6:7], v[62:63], v[30:31], v[6:7] op_sel_hi:[0,1,1]
	v_add_f32_e32 v24, v5, v24
	v_add_f32_e32 v24, v6, v24
	v_add_f32_e32 v24, v7, v24
	v_pk_fma_f32 v[8:9], v[62:63], v[32:33], v[8:9] op_sel_hi:[0,1,1]
	v_add_f32_e32 v24, v24, v8
	v_pk_fma_f32 v[10:11], v[62:63], v[34:35], v[10:11] op_sel_hi:[0,1,1]
	v_add_f32_e32 v24, v9, v24
	v_add_f32_e32 v24, v10, v24
	v_add_f32_e32 v24, v11, v24
	v_pk_fma_f32 v[12:13], v[62:63], v[40:41], v[12:13] op_sel_hi:[0,1,1]
	v_add_f32_e32 v24, v24, v12
	v_pk_fma_f32 v[14:15], v[62:63], v[42:43], v[14:15] op_sel_hi:[0,1,1]
	v_add_f32_e32 v24, v13, v24
	v_lshl_add_u64 v[48:49], v[70:71], 2, s[6:7]
	v_add_f32_e32 v24, v14, v24
	v_lshl_add_u64 v[48:49], v[48:49], 0, v[74:75]
	v_add_f32_e32 v28, v15, v24
	v_pk_fma_f32 v[26:27], v[62:63], v[44:45], v[20:21] op_sel_hi:[0,1,1]
	global_load_dwordx4 v[72:75], v[48:49], off
	v_add_f32_e32 v20, v28, v26
	v_pk_fma_f32 v[24:25], v[62:63], v[46:47], v[22:23] op_sel_hi:[0,1,1]
	v_add_f32_e32 v20, v27, v20
	v_add_f32_e32 v20, v24, v20
	v_add_f32_e32 v20, v25, v20
	v_add_f32_e32 v20, v20, v54
	v_add_f32_e32 v20, v55, v20
	v_mul_f32_e32 v68, 0xbfb8aa3b, v83
	v_mul_f32_e32 v69, 0xbfb8aa3b, v86
	v_add_f32_e32 v20, v56, v20
	v_exp_f32_e32 v68, v68
	v_exp_f32_e32 v69, v69
	v_add_f32_e32 v20, v57, v20
	v_add_f32_e32 v20, v20, v60
	v_add_f32_e32 v20, v61, v20
	v_add_f32_e32 v20, v58, v20
	v_pk_add_f32 v[68:69], v[68:69], 1.0 op_sel_hi:[1,0]
	v_add_f32_e32 v20, v59, v20
	v_div_scale_f32 v39, s[0:1], v69, v69, v86
	ds_bpermute_b32 v21, v76, v20
	v_rcp_f32_e32 v84, v39
	v_lshl_add_u64 v[50:51], v[102:103], 0, s[46:47]
	v_fma_f32 v77, -v39, v84, 1.0
	s_waitcnt lgkmcnt(0)
	v_add_f32_e32 v20, v20, v21
	v_fmac_f32_e32 v84, v77, v84
	v_div_scale_f32 v77, vcc, v86, v69, v86
	ds_bpermute_b32 v21, v63, v20
	v_mul_f32_e32 v85, v77, v84
	v_fma_f32 v87, -v39, v85, v77
	v_fmac_f32_e32 v85, v87, v84
	v_fma_f32 v22, -v39, v85, v77
	v_div_fmas_f32 v22, v22, v84, v85
	s_waitcnt lgkmcnt(0)
	v_add_f32_e32 v20, v20, v21
	v_div_fixup_f32 v29, v22, v69, v86
	v_mul_f32_e32 v28, 0x3c000000, v20
	v_pk_add_f32 v[32:33], v[16:17], v[28:29] op_sel_hi:[1,0] neg_lo:[0,1] neg_hi:[0,1]
	v_pk_add_f32 v[38:39], v[18:19], v[28:29] op_sel_hi:[1,0] neg_lo:[0,1] neg_hi:[0,1]
	v_pk_mul_f32 v[34:35], v[32:33], v[32:33]
	v_pk_mul_f32 v[40:41], v[38:39], v[38:39]
	v_pk_add_f32 v[42:43], v[0:1], v[28:29] op_sel_hi:[1,0] neg_lo:[0,1] neg_hi:[0,1]
	v_pk_add_f32 v[46:47], v[2:3], v[28:29] op_sel_hi:[1,0] neg_lo:[0,1] neg_hi:[0,1]
	v_pk_add_f32 v[84:85], v[4:5], v[28:29] op_sel_hi:[1,0] neg_lo:[0,1] neg_hi:[0,1]
	v_pk_add_f32 v[88:89], v[6:7], v[28:29] op_sel_hi:[1,0] neg_lo:[0,1] neg_hi:[0,1]
	v_pk_add_f32 v[22:23], v[8:9], v[28:29] op_sel_hi:[1,0] neg_lo:[0,1] neg_hi:[0,1]
	v_pk_add_f32 v[20:21], v[10:11], v[28:29] op_sel_hi:[1,0] neg_lo:[0,1] neg_hi:[0,1]
	v_pk_add_f32 v[18:19], v[12:13], v[28:29] op_sel_hi:[1,0] neg_lo:[0,1] neg_hi:[0,1]
	v_pk_add_f32 v[16:17], v[14:15], v[28:29] op_sel_hi:[1,0] neg_lo:[0,1] neg_hi:[0,1]
	v_pk_add_f32 v[14:15], v[26:27], v[28:29] op_sel_hi:[1,0] neg_lo:[0,1] neg_hi:[0,1]
	v_pk_add_f32 v[12:13], v[24:25], v[28:29] op_sel_hi:[1,0] neg_lo:[0,1] neg_hi:[0,1]
	v_pk_add_f32 v[4:5], v[60:61], v[28:29] op_sel_hi:[1,0] neg_lo:[0,1] neg_hi:[0,1]
	v_pk_add_f32 v[0:1], v[58:59], v[28:29] op_sel_hi:[1,0] neg_lo:[0,1] neg_hi:[0,1]
	v_pk_add_f32 v[8:9], v[56:57], v[28:29] op_sel_hi:[1,0] neg_lo:[0,1] neg_hi:[0,1]
	v_pk_add_f32 v[10:11], v[54:55], v[28:29] op_sel_hi:[1,0] neg_lo:[0,1] neg_hi:[0,1]
	v_add_f32_e32 v28, v34, v35
	v_add_f32_e32 v28, v40, v28
	v_pk_mul_f32 v[44:45], v[42:43], v[42:43]
	v_add_f32_e32 v28, v41, v28
	v_add_f32_e32 v28, v44, v28
	v_pk_mul_f32 v[2:3], v[46:47], v[46:47]
	v_add_f32_e32 v28, v45, v28
	v_add_f32_e32 v2, v2, v28
	v_pk_mul_f32 v[86:87], v[84:85], v[84:85]
	v_add_f32_e32 v2, v3, v2
	v_add_f32_e32 v2, v86, v2
	v_pk_mul_f32 v[6:7], v[88:89], v[88:89]
	v_add_f32_e32 v2, v87, v2
	v_add_f32_e32 v2, v6, v2
	v_pk_mul_f32 v[90:91], v[22:23], v[22:23]
	v_add_f32_e32 v2, v7, v2
	v_add_f32_e32 v2, v90, v2
	v_pk_mul_f32 v[92:93], v[20:21], v[20:21]
	v_add_f32_e32 v2, v91, v2
	v_add_f32_e32 v2, v92, v2
	v_pk_mul_f32 v[94:95], v[18:19], v[18:19]
	v_add_f32_e32 v2, v93, v2
	v_add_f32_e32 v2, v94, v2
	v_pk_mul_f32 v[96:97], v[16:17], v[16:17]
	v_add_f32_e32 v2, v95, v2
	v_add_f32_e32 v2, v96, v2
	v_pk_mul_f32 v[26:27], v[14:15], v[14:15]
	v_add_f32_e32 v2, v97, v2
	v_add_f32_e32 v2, v26, v2
	v_pk_mul_f32 v[24:25], v[12:13], v[12:13]
	v_add_f32_e32 v2, v27, v2
	v_add_f32_e32 v2, v24, v2
	v_pk_mul_f32 v[54:55], v[10:11], v[10:11]
	v_add_f32_e32 v2, v25, v2
	v_add_f32_e32 v2, v54, v2
	v_pk_mul_f32 v[56:57], v[8:9], v[8:9]
	v_add_f32_e32 v2, v55, v2
	v_add_f32_e32 v2, v56, v2
	v_pk_mul_f32 v[60:61], v[4:5], v[4:5]
	v_add_f32_e32 v2, v57, v2
	v_add_f32_e32 v2, v60, v2
	v_pk_mul_f32 v[58:59], v[0:1], v[0:1]
	v_add_f32_e32 v2, v61, v2
	v_add_f32_e32 v2, v58, v2
	v_add_f32_e32 v2, v59, v2
	ds_bpermute_b32 v3, v76, v2
	v_div_scale_f32 v62, s[0:1], v68, v68, v83
	v_rcp_f32_e32 v69, v62
	s_waitcnt vmcnt(0)
	v_lshlrev_b32_e32 v40, 16, v31
	s_waitcnt lgkmcnt(0)
	v_add_f32_e32 v2, v2, v3
	ds_bpermute_b32 v3, v63, v2
	v_fma_f32 v6, -v62, v69, 1.0
	v_fmac_f32_e32 v69, v6, v69
	v_div_scale_f32 v6, vcc, v83, v68, v83
	s_waitcnt lgkmcnt(0)
	v_add_f32_e32 v2, v2, v3
	v_fmamk_f32 v2, v2, 0x3c000000, v81
	v_mul_f32_e32 v7, v6, v69
	v_mul_f32_e32 v3, 0x4b800000, v2
	v_cmp_gt_f32_e64 s[0:1], s54, v2
	v_fma_f32 v24, -v62, v7, v6
	v_fmac_f32_e32 v7, v24, v69
	v_cndmask_b32_e64 v2, v2, v3, s[0:1]
	v_rsq_f32_e32 v24, v2
	v_fma_f32 v6, -v62, v7, v6
	v_div_fmas_f32 v2, v6, v69, v7
	v_div_fixup_f32 v28, v2, v68, v83
	v_mul_f32_e32 v6, 0x45800000, v24
	v_cndmask_b32_e64 v6, v24, v6, s[0:1]
	v_pk_mul_f32 v[24:25], v[32:33], v[6:7] op_sel_hi:[1,0]
	v_pk_mul_f32 v[26:27], v[38:39], v[6:7] op_sel_hi:[1,0]
	v_pk_mul_f32 v[24:25], v[72:73], v[24:25]
	v_pk_mul_f32 v[26:27], v[74:75], v[26:27]
	v_pk_mul_f32 v[24:25], v[36:37], v[24:25]
	v_pk_mul_f32 v[26:27], v[28:29], v[26:27]
	v_lshl_add_u64 v[2:3], v[52:53], 0, v[64:65]
	v_bfe_u32 v180, v154, 4, 2
	v_lshlrev_b32_e32 v180, 3, v180
	v_mov_b32_e32 v181, 0
	v_lshl_add_u64 v[180:181], v[2:3], 0, v[180:181]
	v_cvt_pk_bf16_f32 v24, v24, v25
	v_cvt_pk_bf16_f32 v25, v26, v27
	v_lshlrev_b32_e32 v32, 16, v186
	v_and_b32_e32 v33, 0xffff0000, v186
	v_lshlrev_b32_e32 v34, 16, v187
	v_and_b32_e32 v35, 0xffff0000, v187
	v_mul_f32_e32 v36, 0xbfb8aa3b, v32
	v_mul_f32_e32 v37, 0xbfb8aa3b, v33
	v_mul_f32_e32 v38, 0xbfb8aa3b, v34
	v_mul_f32_e32 v39, 0xbfb8aa3b, v35
	v_exp_f32_e32 v36, v36
	v_exp_f32_e32 v37, v37
	v_exp_f32_e32 v38, v38
	v_exp_f32_e32 v39, v39
	v_pk_mul_f32 v[42:43], v[42:43], v[6:7] op_sel_hi:[1,0]
	v_pk_mul_f32 v[46:47], v[46:47], v[6:7] op_sel_hi:[1,0]
	v_pk_add_f32 v[36:37], v[36:37], 1.0 op_sel_hi:[1,0]
	v_pk_add_f32 v[38:39], v[38:39], 1.0 op_sel_hi:[1,0]
	v_pk_mul_f32 v[42:43], v[204:205], v[42:43]
	v_pk_mul_f32 v[46:47], v[206:207], v[46:47]
	v_rcp_f32_e32 v36, v36
	v_rcp_f32_e32 v37, v37
	v_rcp_f32_e32 v38, v38
	v_rcp_f32_e32 v39, v39
	v_pk_mul_f32 v[32:33], v[32:33], v[36:37]
	v_pk_mul_f32 v[34:35], v[34:35], v[38:39]
	v_pk_mul_f32 v[42:43], v[32:33], v[42:43]
	v_pk_mul_f32 v[46:47], v[34:35], v[46:47]
	v_cvt_pk_bf16_f32 v26, v42, v43
	v_cvt_pk_bf16_f32 v27, v46, v47
	s_nop 1
	v_permlane32_swap_b32_e32 v24, v26
	v_permlane32_swap_b32_e32 v25, v27
	s_nop 0
	v_permlane16_swap_b32_e32 v24, v26
	v_permlane16_swap_b32_e32 v25, v27
	global_store_dwordx4 v[180:181], v[24:27], off
	v_lshlrev_b32_e32 v172, 16, v188
	v_and_b32_e32 v173, 0xffff0000, v188
	v_lshlrev_b32_e32 v174, 16, v189
	v_and_b32_e32 v175, 0xffff0000, v189
	v_mul_f32_e32 v176, 0xbfb8aa3b, v172
	v_mul_f32_e32 v177, 0xbfb8aa3b, v173
	v_mul_f32_e32 v178, 0xbfb8aa3b, v174
	v_mul_f32_e32 v179, 0xbfb8aa3b, v175
	v_exp_f32_e32 v176, v176
	v_exp_f32_e32 v177, v177
	v_exp_f32_e32 v178, v178
	v_exp_f32_e32 v179, v179
	v_pk_mul_f32 v[84:85], v[84:85], v[6:7] op_sel_hi:[1,0]
	v_pk_mul_f32 v[88:89], v[88:89], v[6:7] op_sel_hi:[1,0]
	v_pk_add_f32 v[176:177], v[176:177], 1.0 op_sel_hi:[1,0]
	v_pk_add_f32 v[178:179], v[178:179], 1.0 op_sel_hi:[1,0]
	v_pk_mul_f32 v[84:85], v[208:209], v[84:85]
	v_pk_mul_f32 v[88:89], v[210:211], v[88:89]
	v_rcp_f32_e32 v176, v176
	v_rcp_f32_e32 v177, v177
	v_rcp_f32_e32 v178, v178
	v_rcp_f32_e32 v179, v179
	v_pk_mul_f32 v[172:173], v[172:173], v[176:177]
	v_pk_mul_f32 v[174:175], v[174:175], v[178:179]
	v_pk_mul_f32 v[84:85], v[172:173], v[84:85]
	v_pk_mul_f32 v[88:89], v[174:175], v[88:89]
	v_cvt_pk_bf16_f32 v160, v84, v85
	v_cvt_pk_bf16_f32 v161, v88, v89
	v_lshlrev_b32_e32 v32, 16, v190
	v_and_b32_e32 v33, 0xffff0000, v190
	v_lshlrev_b32_e32 v34, 16, v191
	v_and_b32_e32 v35, 0xffff0000, v191
	v_mul_f32_e32 v36, 0xbfb8aa3b, v32
	v_mul_f32_e32 v37, 0xbfb8aa3b, v33
	v_mul_f32_e32 v38, 0xbfb8aa3b, v34
	v_mul_f32_e32 v39, 0xbfb8aa3b, v35
	v_exp_f32_e32 v36, v36
	v_exp_f32_e32 v37, v37
	v_exp_f32_e32 v38, v38
	v_exp_f32_e32 v39, v39
	v_pk_mul_f32 v[22:23], v[22:23], v[6:7] op_sel_hi:[1,0]
	v_pk_mul_f32 v[20:21], v[20:21], v[6:7] op_sel_hi:[1,0]
	v_pk_add_f32 v[36:37], v[36:37], 1.0 op_sel_hi:[1,0]
	v_pk_add_f32 v[38:39], v[38:39], 1.0 op_sel_hi:[1,0]
	v_pk_mul_f32 v[22:23], v[212:213], v[22:23]
	v_pk_mul_f32 v[20:21], v[214:215], v[20:21]
	v_rcp_f32_e32 v36, v36
	v_rcp_f32_e32 v37, v37
	v_rcp_f32_e32 v38, v38
	v_rcp_f32_e32 v39, v39
	v_pk_mul_f32 v[32:33], v[32:33], v[36:37]
	v_pk_mul_f32 v[34:35], v[34:35], v[38:39]
	v_pk_mul_f32 v[22:23], v[32:33], v[22:23]
	v_pk_mul_f32 v[20:21], v[34:35], v[20:21]
	v_cvt_pk_bf16_f32 v162, v22, v23
	v_cvt_pk_bf16_f32 v163, v20, v21
	s_nop 1
	v_permlane32_swap_b32_e32 v160, v162
	v_permlane32_swap_b32_e32 v161, v163
	s_nop 0
	v_permlane16_swap_b32_e32 v160, v162
	v_permlane16_swap_b32_e32 v161, v163
	global_store_dwordx4 v[180:181], v[160:163], off offset:64
	v_lshlrev_b32_e32 v172, 16, v192
	v_and_b32_e32 v173, 0xffff0000, v192
	v_lshlrev_b32_e32 v174, 16, v193
	v_and_b32_e32 v175, 0xffff0000, v193
	v_mul_f32_e32 v176, 0xbfb8aa3b, v172
	v_mul_f32_e32 v177, 0xbfb8aa3b, v173
	v_mul_f32_e32 v178, 0xbfb8aa3b, v174
	v_mul_f32_e32 v179, 0xbfb8aa3b, v175
	v_exp_f32_e32 v176, v176
	v_exp_f32_e32 v177, v177
	v_exp_f32_e32 v178, v178
	v_exp_f32_e32 v179, v179
	v_pk_mul_f32 v[18:19], v[18:19], v[6:7] op_sel_hi:[1,0]
	v_pk_mul_f32 v[16:17], v[16:17], v[6:7] op_sel_hi:[1,0]
	v_pk_add_f32 v[176:177], v[176:177], 1.0 op_sel_hi:[1,0]
	v_pk_add_f32 v[178:179], v[178:179], 1.0 op_sel_hi:[1,0]
	v_pk_mul_f32 v[18:19], v[216:217], v[18:19]
	v_pk_mul_f32 v[16:17], v[218:219], v[16:17]
	v_rcp_f32_e32 v176, v176
	v_rcp_f32_e32 v177, v177
	v_rcp_f32_e32 v178, v178
	v_rcp_f32_e32 v179, v179
	v_pk_mul_f32 v[172:173], v[172:173], v[176:177]
	v_pk_mul_f32 v[174:175], v[174:175], v[178:179]
	v_pk_mul_f32 v[18:19], v[172:173], v[18:19]
	v_pk_mul_f32 v[16:17], v[174:175], v[16:17]
	v_cvt_pk_bf16_f32 v164, v18, v19
	v_cvt_pk_bf16_f32 v165, v16, v17
	v_lshlrev_b32_e32 v32, 16, v194
	v_and_b32_e32 v33, 0xffff0000, v194
	v_lshlrev_b32_e32 v34, 16, v195
	v_and_b32_e32 v35, 0xffff0000, v195
	v_mul_f32_e32 v36, 0xbfb8aa3b, v32
	v_mul_f32_e32 v37, 0xbfb8aa3b, v33
	v_mul_f32_e32 v38, 0xbfb8aa3b, v34
	v_mul_f32_e32 v39, 0xbfb8aa3b, v35
	v_exp_f32_e32 v36, v36
	v_exp_f32_e32 v37, v37
	v_exp_f32_e32 v38, v38
	v_exp_f32_e32 v39, v39
	v_pk_mul_f32 v[14:15], v[14:15], v[6:7] op_sel_hi:[1,0]
	v_pk_mul_f32 v[12:13], v[12:13], v[6:7] op_sel_hi:[1,0]
	v_pk_add_f32 v[36:37], v[36:37], 1.0 op_sel_hi:[1,0]
	v_pk_add_f32 v[38:39], v[38:39], 1.0 op_sel_hi:[1,0]
	v_pk_mul_f32 v[14:15], v[220:221], v[14:15]
	v_pk_mul_f32 v[12:13], v[222:223], v[12:13]
	v_rcp_f32_e32 v36, v36
	v_rcp_f32_e32 v37, v37
	v_rcp_f32_e32 v38, v38
	v_rcp_f32_e32 v39, v39
	v_pk_mul_f32 v[32:33], v[32:33], v[36:37]
	v_pk_mul_f32 v[34:35], v[34:35], v[38:39]
	v_pk_mul_f32 v[14:15], v[32:33], v[14:15]
	v_pk_mul_f32 v[12:13], v[34:35], v[12:13]
	v_cvt_pk_bf16_f32 v166, v14, v15
	v_cvt_pk_bf16_f32 v167, v12, v13
	s_nop 1
	v_permlane32_swap_b32_e32 v164, v166
	v_permlane32_swap_b32_e32 v165, v167
	s_nop 0
	v_permlane16_swap_b32_e32 v164, v166
	v_permlane16_swap_b32_e32 v165, v167
	global_store_dwordx4 v[180:181], v[164:167], off offset:128
	v_lshlrev_b32_e32 v172, 16, v196
	v_and_b32_e32 v173, 0xffff0000, v196
	v_lshlrev_b32_e32 v174, 16, v197
	v_and_b32_e32 v175, 0xffff0000, v197
	v_mul_f32_e32 v176, 0xbfb8aa3b, v172
	v_mul_f32_e32 v177, 0xbfb8aa3b, v173
	v_mul_f32_e32 v178, 0xbfb8aa3b, v174
	v_mul_f32_e32 v179, 0xbfb8aa3b, v175
	v_exp_f32_e32 v176, v176
	v_exp_f32_e32 v177, v177
	v_exp_f32_e32 v178, v178
	v_exp_f32_e32 v179, v179
	v_pk_mul_f32 v[10:11], v[10:11], v[6:7] op_sel_hi:[1,0]
	v_pk_mul_f32 v[8:9], v[8:9], v[6:7] op_sel_hi:[1,0]
	v_pk_add_f32 v[176:177], v[176:177], 1.0 op_sel_hi:[1,0]
	v_pk_add_f32 v[178:179], v[178:179], 1.0 op_sel_hi:[1,0]
	v_pk_mul_f32 v[10:11], v[224:225], v[10:11]
	v_pk_mul_f32 v[8:9], v[226:227], v[8:9]
	v_rcp_f32_e32 v176, v176
	v_rcp_f32_e32 v177, v177
	v_rcp_f32_e32 v178, v178
	v_rcp_f32_e32 v179, v179
	v_pk_mul_f32 v[172:173], v[172:173], v[176:177]
	v_pk_mul_f32 v[174:175], v[174:175], v[178:179]
	v_pk_mul_f32 v[10:11], v[172:173], v[10:11]
	v_pk_mul_f32 v[8:9], v[174:175], v[8:9]
	v_cvt_pk_bf16_f32 v168, v10, v11
	v_cvt_pk_bf16_f32 v169, v8, v9
	v_lshlrev_b32_e32 v32, 16, v198
	v_and_b32_e32 v33, 0xffff0000, v198
	v_lshlrev_b32_e32 v34, 16, v199
	v_and_b32_e32 v35, 0xffff0000, v199
	v_mul_f32_e32 v36, 0xbfb8aa3b, v32
	v_mul_f32_e32 v37, 0xbfb8aa3b, v33
	v_mul_f32_e32 v38, 0xbfb8aa3b, v34
	v_mul_f32_e32 v39, 0xbfb8aa3b, v35
	v_exp_f32_e32 v36, v36
	v_exp_f32_e32 v37, v37
	v_exp_f32_e32 v38, v38
	v_exp_f32_e32 v39, v39
	v_pk_mul_f32 v[4:5], v[4:5], v[6:7] op_sel_hi:[1,0]
	v_pk_mul_f32 v[0:1], v[0:1], v[6:7] op_sel_hi:[1,0]
	v_pk_add_f32 v[36:37], v[36:37], 1.0 op_sel_hi:[1,0]
	v_pk_add_f32 v[38:39], v[38:39], 1.0 op_sel_hi:[1,0]
	v_pk_mul_f32 v[4:5], v[228:229], v[4:5]
	v_pk_mul_f32 v[0:1], v[230:231], v[0:1]
	v_rcp_f32_e32 v36, v36
	v_rcp_f32_e32 v37, v37
	v_rcp_f32_e32 v38, v38
	v_rcp_f32_e32 v39, v39
	v_pk_mul_f32 v[32:33], v[32:33], v[36:37]
	v_pk_mul_f32 v[34:35], v[34:35], v[38:39]
	v_pk_mul_f32 v[4:5], v[32:33], v[4:5]
	v_pk_mul_f32 v[0:1], v[34:35], v[0:1]
	v_cvt_pk_bf16_f32 v170, v4, v5
	v_cvt_pk_bf16_f32 v171, v0, v1
	s_nop 1
	v_permlane32_swap_b32_e32 v168, v170
	v_permlane32_swap_b32_e32 v169, v171
	s_nop 0
	v_permlane16_swap_b32_e32 v168, v170
	v_permlane16_swap_b32_e32 v169, v171
	global_store_dwordx4 v[180:181], v[168:171], off offset:192
	s_waitcnt lgkmcnt(0)
	s_barrier
	s_cbranch_scc1 .LBB0_495
